# kvup row-rms pre-step: ten 16-byte loads of both loop iterations issued up front (one wait chain instead of four round trips)
# speedup vs baseline: 1.0241x; 1.0013x over previous
; DI float bflo(unsigned w) { return __uint_as_float(w << 16); }
; DI float bfhi(unsigned w) { return __uint_as_float(w & 0xffff0000u); }
; DI void phase_kvup(const Prm& p, unsigned char* smem_raw, int l, int& base) {
;     ...
;     {
;       const int row = tid >> 2, qf = tid & 3;
;       const u16* src = p.dckv + (size_t)(m0 + row) * 320 + qf * 80;
;       float ss = 0.f;
; #pragma unroll 5
;       for (int c = 0; c < 10; ++c) {
;         const u32x4 v = *(const u32x4*)(src + c * 8);
; #pragma unroll
;         for (int jj = 0; jj < 4; ++jj) { const float a = bflo(v[jj]), b = bfhi(v[jj]); ss += a * a + b * b; }
;       }
;       ss += __shfl_xor(ss, 1);
;       ss += __shfl_xor(ss, 2);
;       if (qf == 0) st[row] = rsqrtf(ss * (1.f / 320.f) + 1e-6f);
;       __syncthreads();
.LBB0_2062:
	v_lshl_add_u64 v[20:21], v[2:3], 0, 0
	s_mov_b64 s[2:3], 0x50
	v_lshl_add_u64 v[128:129], v[2:3], 0, s[2:3]
	global_load_dwordx4 v[4:7], v[20:21], off offset:48
	global_load_dwordx4 v[8:11], v[20:21], off offset:32
	global_load_dwordx4 v[12:15], v[20:21], off offset:16
	global_load_dwordx4 v[16:19], v[20:21], off
	global_load_dwordx4 v[104:107], v[20:21], off offset:64
	global_load_dwordx4 v[108:111], v[128:129], off offset:48
	global_load_dwordx4 v[112:115], v[128:129], off offset:32
	global_load_dwordx4 v[116:119], v[128:129], off offset:16
	global_load_dwordx4 v[120:123], v[128:129], off
	global_load_dwordx4 v[124:127], v[128:129], off offset:64
	s_waitcnt vmcnt(6)
	v_lshlrev_b32_e32 v22, 16, v16
	v_and_b32_e32 v23, 0xffff0000, v16
	v_pk_mul_f32 v[22:23], v[22:23], v[22:23]
	v_and_b32_e32 v25, 0xffff0000, v18
	v_add_f32_e32 v16, v22, v23
	v_and_b32_e32 v24, 0xffff0000, v17
	v_add_f32_e32 v0, v0, v16
	v_lshlrev_b32_e32 v23, 16, v18
	v_lshlrev_b32_e32 v22, 16, v17
	v_pk_mul_f32 v[16:17], v[24:25], v[24:25]
	v_and_b32_e32 v18, 0xffff0000, v13
	v_pk_fma_f32 v[16:17], v[22:23], v[22:23], v[16:17]
	s_nop 0
	v_add_f32_e32 v0, v16, v0
	v_add_f32_e32 v0, v17, v0
	v_lshlrev_b32_e32 v16, 16, v19
	v_and_b32_e32 v17, 0xffff0000, v19
	v_pk_mul_f32 v[16:17], v[16:17], v[16:17]
	v_and_b32_e32 v19, 0xffff0000, v14
	v_add_f32_e32 v16, v16, v17
	v_add_f32_e32 v0, v16, v0
	v_lshlrev_b32_e32 v16, 16, v12
	v_and_b32_e32 v17, 0xffff0000, v12
	v_pk_mul_f32 v[16:17], v[16:17], v[16:17]
	s_nop 0
	v_add_f32_e32 v12, v16, v17
	v_add_f32_e32 v0, v0, v12
	v_lshlrev_b32_e32 v17, 16, v14
	v_lshlrev_b32_e32 v16, 16, v13
	v_pk_mul_f32 v[12:13], v[18:19], v[18:19]
	v_and_b32_e32 v14, 0xffff0000, v9
	v_pk_fma_f32 v[12:13], v[16:17], v[16:17], v[12:13]
	s_nop 0
	v_add_f32_e32 v0, v12, v0
	v_add_f32_e32 v0, v13, v0
	v_lshlrev_b32_e32 v12, 16, v15
	v_and_b32_e32 v13, 0xffff0000, v15
	v_pk_mul_f32 v[12:13], v[12:13], v[12:13]
	v_and_b32_e32 v15, 0xffff0000, v10
	v_add_f32_e32 v12, v12, v13
	v_add_f32_e32 v0, v12, v0
	v_lshlrev_b32_e32 v12, 16, v8
	v_and_b32_e32 v13, 0xffff0000, v8
	v_pk_mul_f32 v[12:13], v[12:13], v[12:13]
	s_nop 0
	v_add_f32_e32 v8, v12, v13
	v_add_f32_e32 v0, v0, v8
	v_lshlrev_b32_e32 v13, 16, v10
	v_lshlrev_b32_e32 v12, 16, v9
	v_pk_mul_f32 v[8:9], v[14:15], v[14:15]
	v_and_b32_e32 v10, 0xffff0000, v5
	v_pk_fma_f32 v[8:9], v[12:13], v[12:13], v[8:9]
	s_nop 0
	v_add_f32_e32 v0, v8, v0
	v_add_f32_e32 v0, v9, v0
	v_lshlrev_b32_e32 v8, 16, v11
	v_and_b32_e32 v9, 0xffff0000, v11
	v_pk_mul_f32 v[8:9], v[8:9], v[8:9]
	v_and_b32_e32 v11, 0xffff0000, v6
	v_add_f32_e32 v8, v8, v9
	v_add_f32_e32 v0, v8, v0
	v_lshlrev_b32_e32 v8, 16, v4
	v_and_b32_e32 v9, 0xffff0000, v4
	v_pk_mul_f32 v[8:9], v[8:9], v[8:9]
	s_nop 0
	v_add_f32_e32 v4, v8, v9
	v_add_f32_e32 v0, v0, v4
	v_lshlrev_b32_e32 v9, 16, v6
	v_lshlrev_b32_e32 v8, 16, v5
	v_pk_mul_f32 v[4:5], v[10:11], v[10:11]
	s_nop 0
	v_pk_fma_f32 v[4:5], v[8:9], v[8:9], v[4:5]
	s_nop 0
	v_add_f32_e32 v0, v4, v0
	v_add_f32_e32 v0, v5, v0
	v_lshlrev_b32_e32 v4, 16, v7
	v_and_b32_e32 v5, 0xffff0000, v7
	v_pk_mul_f32 v[4:5], v[4:5], v[4:5]
	s_nop 0
	v_add_f32_e32 v4, v4, v5
	v_add_f32_e32 v0, v4, v0
	s_waitcnt vmcnt(5)
	v_lshlrev_b32_e32 v8, 16, v104
	v_and_b32_e32 v9, 0xffff0000, v104
	v_pk_mul_f32 v[8:9], v[8:9], v[8:9]
	v_and_b32_e32 v11, 0xffff0000, v106
	v_add_f32_e32 v104, v8, v9
	v_and_b32_e32 v10, 0xffff0000, v105
	v_add_f32_e32 v0, v0, v104
	v_lshlrev_b32_e32 v9, 16, v106
	v_lshlrev_b32_e32 v8, 16, v105
	v_pk_mul_f32 v[104:105], v[10:11], v[10:11]
	s_nop 0
	v_pk_fma_f32 v[104:105], v[8:9], v[8:9], v[104:105]
	s_nop 0
	v_add_f32_e32 v0, v104, v0
	v_add_f32_e32 v0, v105, v0
	v_lshlrev_b32_e32 v104, 16, v107
	v_and_b32_e32 v105, 0xffff0000, v107
	v_pk_mul_f32 v[104:105], v[104:105], v[104:105]
	s_nop 0
	v_add_f32_e32 v104, v104, v105
	v_add_f32_e32 v0, v104, v0
	s_waitcnt vmcnt(1)
; DI float bflo(unsigned w) { return __uint_as_float(w << 16); }
; DI float bfhi(unsigned w) { return __uint_as_float(w & 0xffff0000u); }
; DI void phase_kvup(const Prm& p, unsigned char* smem_raw, int l, int& base) {
;     ...
;     {
;       const int row = tid >> 2, qf = tid & 3;
;       const u16* src = p.dckv + (size_t)(m0 + row) * 320 + qf * 80;
;       float ss = 0.f;
; #pragma unroll 5
;       for (int c = 0; c < 10; ++c) {
;         const u32x4 v = *(const u32x4*)(src + c * 8);
; #pragma unroll
;         for (int jj = 0; jj < 4; ++jj) { const float a = bflo(v[jj]), b = bfhi(v[jj]); ss += a * a + b * b; }
;       }
;       ss += __shfl_xor(ss, 1);
;       ss += __shfl_xor(ss, 2);
;       if (qf == 0) st[row] = rsqrtf(ss * (1.f / 320.f) + 1e-6f);
;       __syncthreads();
	v_lshlrev_b32_e32 v22, 16, v120
	v_and_b32_e32 v23, 0xffff0000, v120
	v_pk_mul_f32 v[22:23], v[22:23], v[22:23]
	v_and_b32_e32 v25, 0xffff0000, v122
	v_add_f32_e32 v120, v22, v23
	v_and_b32_e32 v24, 0xffff0000, v121
	v_add_f32_e32 v0, v0, v120
	v_lshlrev_b32_e32 v23, 16, v122
	v_lshlrev_b32_e32 v22, 16, v121
	v_pk_mul_f32 v[120:121], v[24:25], v[24:25]
	v_and_b32_e32 v122, 0xffff0000, v117
	v_pk_fma_f32 v[120:121], v[22:23], v[22:23], v[120:121]
	s_nop 0
	v_add_f32_e32 v0, v120, v0
	v_add_f32_e32 v0, v121, v0
	v_lshlrev_b32_e32 v120, 16, v123
	v_and_b32_e32 v121, 0xffff0000, v123
	v_pk_mul_f32 v[120:121], v[120:121], v[120:121]
	v_and_b32_e32 v123, 0xffff0000, v118
	v_add_f32_e32 v120, v120, v121
	v_add_f32_e32 v0, v120, v0
	v_lshlrev_b32_e32 v120, 16, v116
	v_and_b32_e32 v121, 0xffff0000, v116
	v_pk_mul_f32 v[120:121], v[120:121], v[120:121]
	s_nop 0
	v_add_f32_e32 v116, v120, v121
	v_add_f32_e32 v0, v0, v116
	v_lshlrev_b32_e32 v121, 16, v118
	v_lshlrev_b32_e32 v120, 16, v117
	v_pk_mul_f32 v[116:117], v[122:123], v[122:123]
	v_and_b32_e32 v118, 0xffff0000, v113
	v_pk_fma_f32 v[116:117], v[120:121], v[120:121], v[116:117]
	s_nop 0
	v_add_f32_e32 v0, v116, v0
	v_add_f32_e32 v0, v117, v0
	v_lshlrev_b32_e32 v116, 16, v119
	v_and_b32_e32 v117, 0xffff0000, v119
	v_pk_mul_f32 v[116:117], v[116:117], v[116:117]
	v_and_b32_e32 v119, 0xffff0000, v114
	v_add_f32_e32 v116, v116, v117
	v_add_f32_e32 v0, v116, v0
	v_lshlrev_b32_e32 v116, 16, v112
	v_and_b32_e32 v117, 0xffff0000, v112
	v_pk_mul_f32 v[116:117], v[116:117], v[116:117]
	s_nop 0
	v_add_f32_e32 v112, v116, v117
	v_add_f32_e32 v0, v0, v112
	v_lshlrev_b32_e32 v117, 16, v114
	v_lshlrev_b32_e32 v116, 16, v113
	v_pk_mul_f32 v[112:113], v[118:119], v[118:119]
	v_and_b32_e32 v114, 0xffff0000, v109
	v_pk_fma_f32 v[112:113], v[116:117], v[116:117], v[112:113]
	s_nop 0
	v_add_f32_e32 v0, v112, v0
	v_add_f32_e32 v0, v113, v0
	v_lshlrev_b32_e32 v112, 16, v115
	v_and_b32_e32 v113, 0xffff0000, v115
	v_pk_mul_f32 v[112:113], v[112:113], v[112:113]
	v_and_b32_e32 v115, 0xffff0000, v110
	v_add_f32_e32 v112, v112, v113
	v_add_f32_e32 v0, v112, v0
	v_lshlrev_b32_e32 v112, 16, v108
	v_and_b32_e32 v113, 0xffff0000, v108
	v_pk_mul_f32 v[112:113], v[112:113], v[112:113]
	s_nop 0
	v_add_f32_e32 v108, v112, v113
	v_add_f32_e32 v0, v0, v108
	v_lshlrev_b32_e32 v113, 16, v110
	v_lshlrev_b32_e32 v112, 16, v109
	v_pk_mul_f32 v[108:109], v[114:115], v[114:115]
	s_nop 0
	v_pk_fma_f32 v[108:109], v[112:113], v[112:113], v[108:109]
	s_nop 0
	v_add_f32_e32 v0, v108, v0
	v_add_f32_e32 v0, v109, v0
	v_lshlrev_b32_e32 v108, 16, v111
	v_and_b32_e32 v109, 0xffff0000, v111
	v_pk_mul_f32 v[108:109], v[108:109], v[108:109]
	s_nop 0
	v_add_f32_e32 v108, v108, v109
	v_add_f32_e32 v0, v108, v0
	s_waitcnt vmcnt(0)
	v_lshlrev_b32_e32 v8, 16, v124
	v_and_b32_e32 v9, 0xffff0000, v124
	v_pk_mul_f32 v[8:9], v[8:9], v[8:9]
	v_and_b32_e32 v11, 0xffff0000, v126
	v_add_f32_e32 v124, v8, v9
	v_and_b32_e32 v10, 0xffff0000, v125
	v_add_f32_e32 v0, v0, v124
	v_lshlrev_b32_e32 v9, 16, v126
	v_lshlrev_b32_e32 v8, 16, v125
	v_pk_mul_f32 v[124:125], v[10:11], v[10:11]
	s_nop 0
	v_pk_fma_f32 v[124:125], v[8:9], v[8:9], v[124:125]
	s_nop 0
	v_add_f32_e32 v0, v124, v0
	v_add_f32_e32 v0, v125, v0
	v_lshlrev_b32_e32 v124, 16, v127
	v_and_b32_e32 v125, 0xffff0000, v127
	v_pk_mul_f32 v[124:125], v[124:125], v[124:125]
	s_nop 0
	v_add_f32_e32 v124, v124, v125
	v_add_f32_e32 v0, v124, v0
	ds_bpermute_b32 v2, v89, v0
	s_waitcnt lgkmcnt(0)
	v_add_f32_e32 v0, v0, v2
	ds_bpermute_b32 v2, v102, v0
	s_and_saveexec_b64 s[2:3], s[0:1]
	s_cbranch_execz .LBB0_2065
	s_waitcnt lgkmcnt(0)
	v_add_f32_e32 v0, v0, v2
	v_fmamk_f32 v0, v0, 0x3b4ccccd, v225
	v_mul_f32_e32 v2, 0x4b800000, v0
	v_cmp_gt_f32_e32 vcc, s85, v0
	s_nop 1
	v_cndmask_b32_e32 v0, v0, v2, vcc
	v_rsq_f32_e32 v0, v0
	s_nop 0
	v_mul_f32_e32 v2, 0x45800000, v0
	v_cndmask_b32_e32 v0, v0, v2, vcc
	ds_write_b32 v103, v0
